# v55 + saddr-form LDS-DMA loads also in the pool GEMM and PLE GEMM K-loops of P3b
# speedup vs baseline: 1.0040x; 1.0040x over previous
.LBB0_948:
	s_add_u32 s60, s36, s59
	ds_read_b128 v[128:131], v157
	ds_read_b128 v[132:135], v157 offset:1024
	ds_read_b128 v[150:153], v157 offset:2048
	ds_read_b128 v[160:163], v157 offset:3072
	ds_read_b128 v[164:167], v158
	ds_read_b128 v[168:171], v158 offset:1024
	ds_read_b128 v[172:175], v158 offset:2048
	ds_read_b128 v[176:179], v158 offset:3072
	s_addc_u32 s61, s37, 0
	s_add_u32 s62, s60, 0x100
	s_addc_u32 s63, s61, 0
	s_and_b64 s[38:39], s[16:17], exec
	s_cselect_b32 s39, s29, s63
	s_cselect_b32 s38, s28, s62
	s_add_u32 s59, s34, s59
	s_addc_u32 s62, s35, 0
	s_add_u32 s59, s59, 0x100
	s_addc_u32 s62, s62, 0
	s_and_b64 s[16:17], s[16:17], exec
	s_cselect_b32 s17, s25, s62
	s_cselect_b32 s16, s27, s59
	s_add_u32 s60, s60, 0x40080
	s_addc_u32 s61, s61, 0
	s_add_i32 m0, s47, 0xc000
	ds_read_b128 v[180:183], v159
	ds_read_b128 v[184:187], v159 offset:1024
	ds_read_b128 v[188:191], v159 offset:2048
	ds_read_b128 v[192:195], v159 offset:3072
	ds_read_b128 v[196:199], v159 offset:4096
	ds_read_b128 v[200:203], v159 offset:5120
	ds_read_b128 v[206:209], v159 offset:6144
	ds_read_b128 v[210:213], v159 offset:7168
	global_load_lds_dwordx4 v144, s[60:61]
	s_add_i32 m0, s47, 0xe000
	s_nop 0
	global_load_lds_dwordx4 v140, s[60:61]
	s_waitcnt vmcnt(8)
	s_waitcnt lgkmcnt(0)
	s_barrier
	s_setprio 1
	s_waitcnt lgkmcnt(0)
	v_mfma_f32_16x16x32_bf16 v[124:127], v[128:131], v[180:183], v[124:127]
	v_mfma_f32_16x16x32_bf16 v[120:123], v[150:153], v[180:183], v[120:123]
	v_mfma_f32_16x16x32_bf16 v[116:119], v[128:131], v[188:191], v[116:119]
	v_mfma_f32_16x16x32_bf16 v[112:115], v[150:153], v[188:191], v[112:115]
	v_mfma_f32_16x16x32_bf16 v[108:111], v[128:131], v[196:199], v[108:111]
	v_mfma_f32_16x16x32_bf16 v[104:107], v[150:153], v[196:199], v[104:107]
	v_mfma_f32_16x16x32_bf16 v[100:103], v[128:131], v[206:209], v[100:103]
	v_mfma_f32_16x16x32_bf16 v[96:99], v[150:153], v[206:209], v[96:99]
	v_mfma_f32_16x16x32_bf16 v[124:127], v[132:135], v[184:187], v[124:127]
	v_mfma_f32_16x16x32_bf16 v[120:123], v[160:163], v[184:187], v[120:123]
	v_mfma_f32_16x16x32_bf16 v[116:119], v[132:135], v[192:195], v[116:119]
	v_mfma_f32_16x16x32_bf16 v[112:115], v[160:163], v[192:195], v[112:115]
	v_mfma_f32_16x16x32_bf16 v[108:111], v[132:135], v[200:203], v[108:111]
	v_mfma_f32_16x16x32_bf16 v[104:107], v[160:163], v[200:203], v[104:107]
	v_mfma_f32_16x16x32_bf16 v[100:103], v[132:135], v[210:213], v[100:103]
	v_mfma_f32_16x16x32_bf16 v[96:99], v[160:163], v[210:213], v[96:99]
	s_setprio 0
	s_setprio 1
	v_mfma_f32_16x16x32_bf16 v[60:63], v[164:167], v[180:183], v[60:63]
	v_mfma_f32_16x16x32_bf16 v[56:59], v[172:175], v[180:183], v[56:59]
	v_mfma_f32_16x16x32_bf16 v[52:55], v[164:167], v[188:191], v[52:55]
	v_mfma_f32_16x16x32_bf16 v[48:51], v[172:175], v[188:191], v[48:51]
	v_mfma_f32_16x16x32_bf16 v[44:47], v[164:167], v[196:199], v[44:47]
	v_mfma_f32_16x16x32_bf16 v[40:43], v[172:175], v[196:199], v[40:43]
	v_mfma_f32_16x16x32_bf16 v[36:39], v[164:167], v[206:209], v[36:39]
	v_mfma_f32_16x16x32_bf16 v[32:35], v[172:175], v[206:209], v[32:35]
	v_mfma_f32_16x16x32_bf16 v[60:63], v[168:171], v[184:187], v[60:63]
	v_mfma_f32_16x16x32_bf16 v[56:59], v[176:179], v[184:187], v[56:59]
	v_mfma_f32_16x16x32_bf16 v[52:55], v[168:171], v[192:195], v[52:55]
	v_mfma_f32_16x16x32_bf16 v[48:51], v[176:179], v[192:195], v[48:51]
	v_mfma_f32_16x16x32_bf16 v[44:47], v[168:171], v[200:203], v[44:47]
	v_mfma_f32_16x16x32_bf16 v[40:43], v[176:179], v[200:203], v[40:43]
	v_mfma_f32_16x16x32_bf16 v[36:39], v[168:171], v[210:213], v[36:39]
	v_mfma_f32_16x16x32_bf16 v[32:35], v[176:179], v[210:213], v[32:35]
	s_setprio 0
	s_barrier
	s_add_i32 s59, s55, s93
	s_mov_b32 m0, s59
	ds_read_b128 v[180:183], v159 offset:16384
	ds_read_b128 v[184:187], v159 offset:17408
	ds_read_b128 v[188:191], v159 offset:18432
	ds_read_b128 v[192:195], v159 offset:19456
	ds_read_b128 v[196:199], v159 offset:20480
	ds_read_b128 v[200:203], v159 offset:21504
	ds_read_b128 v[206:209], v159 offset:22528
	ds_read_b128 v[210:213], v159 offset:23552
	global_load_lds_dwordx4 v142, s[16:17]
	s_add_i32 m0, s59, 0x2000
	s_add_u32 s60, s16, 0x10000
	v_lshl_add_u64 v[214:215], s[16:17], 0, v[138:139]
	s_addc_u32 s61, s17, 0
	s_add_i32 s59, s56, s93
	global_load_lds_dwordx4 v138, s[16:17]
	s_mov_b32 m0, s59
	v_lshl_add_u64 v[218:219], s[38:39], 0, v[140:141]
	global_load_lds_dwordx4 v142, s[60:61]
	s_add_i32 m0, s59, 0x2000
	s_nop 0
	global_load_lds_dwordx4 v138, s[60:61]
	v_lshl_add_u64 v[216:217], s[38:39], 0, v[144:145]
	s_mov_b32 m0, s47
	s_nop 0
	global_load_lds_dwordx4 v144, s[38:39]
	s_mov_b32 m0, s48
	s_nop 0
	global_load_lds_dwordx4 v140, s[38:39]
	s_waitcnt vmcnt(8)
	s_waitcnt lgkmcnt(0)
	s_barrier
	s_setprio 1
	s_waitcnt lgkmcnt(0)
	v_mfma_f32_16x16x32_bf16 v[92:95], v[128:131], v[180:183], v[92:95]
	v_mfma_f32_16x16x32_bf16 v[88:91], v[150:153], v[180:183], v[88:91]
	v_mfma_f32_16x16x32_bf16 v[84:87], v[128:131], v[188:191], v[84:87]
	v_mfma_f32_16x16x32_bf16 v[80:83], v[150:153], v[188:191], v[80:83]
	v_mfma_f32_16x16x32_bf16 v[76:79], v[128:131], v[196:199], v[76:79]
	v_mfma_f32_16x16x32_bf16 v[72:75], v[150:153], v[196:199], v[72:75]
	v_mfma_f32_16x16x32_bf16 v[68:71], v[128:131], v[206:209], v[68:71]
	v_mfma_f32_16x16x32_bf16 v[64:67], v[150:153], v[206:209], v[64:67]
	v_mfma_f32_16x16x32_bf16 v[92:95], v[132:135], v[184:187], v[92:95]
	v_mfma_f32_16x16x32_bf16 v[88:91], v[160:163], v[184:187], v[88:91]
	v_mfma_f32_16x16x32_bf16 v[84:87], v[132:135], v[192:195], v[84:87]
	v_mfma_f32_16x16x32_bf16 v[80:83], v[160:163], v[192:195], v[80:83]
	v_mfma_f32_16x16x32_bf16 v[76:79], v[132:135], v[200:203], v[76:79]
	v_mfma_f32_16x16x32_bf16 v[72:75], v[160:163], v[200:203], v[72:75]
	v_mfma_f32_16x16x32_bf16 v[68:71], v[132:135], v[210:213], v[68:71]
	v_mfma_f32_16x16x32_bf16 v[64:67], v[160:163], v[210:213], v[64:67]
	s_setprio 0
	s_setprio 1
	v_mfma_f32_16x16x32_bf16 v[28:31], v[164:167], v[180:183], v[28:31]
	v_mfma_f32_16x16x32_bf16 v[24:27], v[172:175], v[180:183], v[24:27]
	v_mfma_f32_16x16x32_bf16 v[20:23], v[164:167], v[188:191], v[20:23]
	v_mfma_f32_16x16x32_bf16 v[16:19], v[172:175], v[188:191], v[16:19]
	v_mfma_f32_16x16x32_bf16 v[12:15], v[164:167], v[196:199], v[12:15]
	v_mfma_f32_16x16x32_bf16 v[8:11], v[172:175], v[196:199], v[8:11]
	v_mfma_f32_16x16x32_bf16 v[4:7], v[164:167], v[206:209], v[4:7]
	v_mfma_f32_16x16x32_bf16 v[0:3], v[172:175], v[206:209], v[0:3]
	v_mfma_f32_16x16x32_bf16 v[28:31], v[168:171], v[184:187], v[28:31]
	v_mfma_f32_16x16x32_bf16 v[24:27], v[176:179], v[184:187], v[24:27]
	v_mfma_f32_16x16x32_bf16 v[20:23], v[168:171], v[192:195], v[20:23]
	v_mfma_f32_16x16x32_bf16 v[16:19], v[176:179], v[192:195], v[16:19]
	v_mfma_f32_16x16x32_bf16 v[12:15], v[168:171], v[200:203], v[12:15]
	v_mfma_f32_16x16x32_bf16 v[8:11], v[176:179], v[200:203], v[8:11]
	v_mfma_f32_16x16x32_bf16 v[4:7], v[168:171], v[210:213], v[4:7]
	v_mfma_f32_16x16x32_bf16 v[0:3], v[176:179], v[210:213], v[0:3]
	s_setprio 0
	s_barrier
	s_add_i32 s59, 0, 0x18000
	s_add_i32 s60, 0, 0x1c000
	v_add_u32_e32 v160, s59, v155
	v_add_u32_e32 v176, s60, v155
	ds_read_b128 v[128:131], v160
	ds_read_b128 v[132:135], v160 offset:1024
	ds_read_b128 v[150:153], v160 offset:2048
	ds_read_b128 v[160:163], v160 offset:3072
	ds_read_b128 v[164:167], v176
	ds_read_b128 v[168:171], v176 offset:1024
	ds_read_b128 v[172:175], v176 offset:2048
	ds_read_b128 v[176:179], v176 offset:3072
	s_add_u32 s38, s38, 0x40000
	s_addc_u32 s39, s39, 0
	s_mov_b32 m0, s49
	ds_read_b128 v[180:183], v159 offset:32768
	ds_read_b128 v[184:187], v159 offset:33792
	ds_read_b128 v[188:191], v159 offset:34816
	ds_read_b128 v[192:195], v159 offset:35840
	ds_read_b128 v[196:199], v159 offset:36864
	ds_read_b128 v[200:203], v159 offset:37888
	ds_read_b128 v[206:209], v159 offset:38912
	ds_read_b128 v[210:213], v159 offset:39936
	global_load_lds_dwordx4 v144, s[38:39]
	s_mov_b32 m0, s50
	s_nop 0
	global_load_lds_dwordx4 v140, s[38:39]
	s_waitcnt vmcnt(8)
	s_waitcnt lgkmcnt(0)
	s_barrier
	s_setprio 1
	s_waitcnt lgkmcnt(0)
	v_mfma_f32_16x16x32_bf16 v[124:127], v[128:131], v[180:183], v[124:127]
	v_mfma_f32_16x16x32_bf16 v[120:123], v[150:153], v[180:183], v[120:123]
	v_mfma_f32_16x16x32_bf16 v[116:119], v[128:131], v[188:191], v[116:119]
	v_mfma_f32_16x16x32_bf16 v[112:115], v[150:153], v[188:191], v[112:115]
	v_mfma_f32_16x16x32_bf16 v[108:111], v[128:131], v[196:199], v[108:111]
	v_mfma_f32_16x16x32_bf16 v[104:107], v[150:153], v[196:199], v[104:107]
	v_mfma_f32_16x16x32_bf16 v[100:103], v[128:131], v[206:209], v[100:103]
	v_mfma_f32_16x16x32_bf16 v[96:99], v[150:153], v[206:209], v[96:99]
	v_mfma_f32_16x16x32_bf16 v[124:127], v[132:135], v[184:187], v[124:127]
	v_mfma_f32_16x16x32_bf16 v[120:123], v[160:163], v[184:187], v[120:123]
	v_mfma_f32_16x16x32_bf16 v[116:119], v[132:135], v[192:195], v[116:119]
	v_mfma_f32_16x16x32_bf16 v[112:115], v[160:163], v[192:195], v[112:115]
	v_mfma_f32_16x16x32_bf16 v[108:111], v[132:135], v[200:203], v[108:111]
	v_mfma_f32_16x16x32_bf16 v[104:107], v[160:163], v[200:203], v[104:107]
	v_mfma_f32_16x16x32_bf16 v[100:103], v[132:135], v[210:213], v[100:103]
	v_mfma_f32_16x16x32_bf16 v[96:99], v[160:163], v[210:213], v[96:99]
	s_setprio 0
	s_setprio 1
	v_mfma_f32_16x16x32_bf16 v[60:63], v[164:167], v[180:183], v[60:63]
	v_mfma_f32_16x16x32_bf16 v[56:59], v[172:175], v[180:183], v[56:59]
	v_mfma_f32_16x16x32_bf16 v[52:55], v[164:167], v[188:191], v[52:55]
	v_mfma_f32_16x16x32_bf16 v[48:51], v[172:175], v[188:191], v[48:51]
	v_mfma_f32_16x16x32_bf16 v[44:47], v[164:167], v[196:199], v[44:47]
	v_mfma_f32_16x16x32_bf16 v[40:43], v[172:175], v[196:199], v[40:43]
	v_mfma_f32_16x16x32_bf16 v[36:39], v[164:167], v[206:209], v[36:39]
	v_mfma_f32_16x16x32_bf16 v[32:35], v[172:175], v[206:209], v[32:35]
	v_mfma_f32_16x16x32_bf16 v[60:63], v[168:171], v[184:187], v[60:63]
	v_mfma_f32_16x16x32_bf16 v[56:59], v[176:179], v[184:187], v[56:59]
	v_mfma_f32_16x16x32_bf16 v[52:55], v[168:171], v[192:195], v[52:55]
	v_mfma_f32_16x16x32_bf16 v[48:51], v[176:179], v[192:195], v[48:51]
	v_mfma_f32_16x16x32_bf16 v[44:47], v[168:171], v[200:203], v[44:47]
	v_mfma_f32_16x16x32_bf16 v[40:43], v[176:179], v[200:203], v[40:43]
	v_mfma_f32_16x16x32_bf16 v[36:39], v[168:171], v[210:213], v[36:39]
	v_mfma_f32_16x16x32_bf16 v[32:35], v[176:179], v[210:213], v[32:35]
	s_setprio 0
	s_barrier
	s_add_i32 s38, s59, s93
	s_add_i32 m0, s38, 0xffffff80
	ds_read_b128 v[180:183], v159 offset:49152
	ds_read_b128 v[184:187], v159 offset:50176
	ds_read_b128 v[188:191], v159 offset:51200
	ds_read_b128 v[192:195], v159 offset:52224
	ds_read_b128 v[196:199], v159 offset:53248
	ds_read_b128 v[200:203], v159 offset:54272
	ds_read_b128 v[206:209], v159 offset:55296
	ds_read_b128 v[210:213], v159 offset:56320
	global_load_lds_dwordx4 v142, s[16:17] offset:128
	s_add_i32 m0, s38, 0x2000
	s_add_u32 s16, s16, 0x10080
	v_lshl_add_u64 v[136:137], v[214:215], 0, s[18:19]
	s_addc_u32 s17, s17, 0
	s_add_i32 s38, s60, s93
	global_load_lds_dwordx4 v[136:137], off
	s_mov_b32 m0, s38
	s_nop 0
	global_load_lds_dwordx4 v142, s[16:17]
	s_add_i32 m0, s38, 0x2000
	s_nop 0
	global_load_lds_dwordx4 v138, s[16:17]
	v_lshl_add_u64 v[136:137], v[216:217], 0, s[18:19]
	s_mov_b32 m0, s52
	s_nop 0
	global_load_lds_dwordx4 v[136:137], off
	v_lshl_add_u64 v[136:137], v[218:219], 0, s[18:19]
	s_mov_b32 m0, s53
	s_nop 0
	global_load_lds_dwordx4 v[136:137], off
	s_waitcnt vmcnt(8)
	s_waitcnt lgkmcnt(0)
	s_barrier
	s_setprio 1
	s_waitcnt lgkmcnt(0)
	v_mfma_f32_16x16x32_bf16 v[92:95], v[128:131], v[180:183], v[92:95]
	v_mfma_f32_16x16x32_bf16 v[88:91], v[150:153], v[180:183], v[88:91]
	v_mfma_f32_16x16x32_bf16 v[84:87], v[128:131], v[188:191], v[84:87]
	v_mfma_f32_16x16x32_bf16 v[80:83], v[150:153], v[188:191], v[80:83]
	v_mfma_f32_16x16x32_bf16 v[76:79], v[128:131], v[196:199], v[76:79]
	v_mfma_f32_16x16x32_bf16 v[72:75], v[150:153], v[196:199], v[72:75]
	v_mfma_f32_16x16x32_bf16 v[68:71], v[128:131], v[206:209], v[68:71]
	v_mfma_f32_16x16x32_bf16 v[64:67], v[150:153], v[206:209], v[64:67]
	v_mfma_f32_16x16x32_bf16 v[92:95], v[132:135], v[184:187], v[92:95]
	v_mfma_f32_16x16x32_bf16 v[88:91], v[160:163], v[184:187], v[88:91]
	v_mfma_f32_16x16x32_bf16 v[84:87], v[132:135], v[192:195], v[84:87]
	v_mfma_f32_16x16x32_bf16 v[80:83], v[160:163], v[192:195], v[80:83]
	v_mfma_f32_16x16x32_bf16 v[76:79], v[132:135], v[200:203], v[76:79]
	v_mfma_f32_16x16x32_bf16 v[72:75], v[160:163], v[200:203], v[72:75]
	v_mfma_f32_16x16x32_bf16 v[68:71], v[132:135], v[210:213], v[68:71]
	v_mfma_f32_16x16x32_bf16 v[64:67], v[160:163], v[210:213], v[64:67]
	s_setprio 0
	s_setprio 1
	v_mfma_f32_16x16x32_bf16 v[28:31], v[164:167], v[180:183], v[28:31]
	v_mfma_f32_16x16x32_bf16 v[24:27], v[172:175], v[180:183], v[24:27]
	v_mfma_f32_16x16x32_bf16 v[20:23], v[164:167], v[188:191], v[20:23]
	v_mfma_f32_16x16x32_bf16 v[16:19], v[172:175], v[188:191], v[16:19]
	v_mfma_f32_16x16x32_bf16 v[12:15], v[164:167], v[196:199], v[12:15]
	v_mfma_f32_16x16x32_bf16 v[8:11], v[172:175], v[196:199], v[8:11]
	v_mfma_f32_16x16x32_bf16 v[4:7], v[164:167], v[206:209], v[4:7]
	v_mfma_f32_16x16x32_bf16 v[0:3], v[172:175], v[206:209], v[0:3]
	v_mfma_f32_16x16x32_bf16 v[28:31], v[168:171], v[184:187], v[28:31]
	v_mfma_f32_16x16x32_bf16 v[24:27], v[176:179], v[184:187], v[24:27]
	v_mfma_f32_16x16x32_bf16 v[20:23], v[168:171], v[192:195], v[20:23]
	v_mfma_f32_16x16x32_bf16 v[16:19], v[176:179], v[192:195], v[16:19]
	v_mfma_f32_16x16x32_bf16 v[12:15], v[168:171], v[200:203], v[12:15]
	v_mfma_f32_16x16x32_bf16 v[8:11], v[176:179], v[200:203], v[8:11]
	v_mfma_f32_16x16x32_bf16 v[4:7], v[168:171], v[210:213], v[4:7]
	v_mfma_f32_16x16x32_bf16 v[0:3], v[176:179], v[210:213], v[0:3]
	s_setprio 0
	s_barrier
	s_movk_i32 s59, 0x100
	s_and_b64 vcc, exec, s[0:1]
	s_mov_b64 s[16:17], -1
	s_mov_b64 s[0:1], 0
	s_cbranch_vccnz .LBB0_948
	s_andn2_b64 vcc, exec, s[94:95]
	s_cbranch_vccnz .LBB0_951
	s_barrier

.LBB0_971:
	s_add_u32 s57, s28, s56
	ds_read_b128 v[146:149], v143
	ds_read_b128 v[150:153], v143 offset:1024
	ds_read_b128 v[154:157], v143 offset:2048
	ds_read_b128 v[158:161], v143 offset:3072
	ds_read_b128 v[162:165], v144
	ds_read_b128 v[166:169], v144 offset:1024
	ds_read_b128 v[170:173], v144 offset:2048
	ds_read_b128 v[174:177], v144 offset:3072
	s_addc_u32 s58, s29, 0
	s_add_u32 s59, s57, 0x100
	s_addc_u32 s60, s58, 0
	s_and_b64 s[34:35], s[30:31], exec
	s_cselect_b32 s35, s19, s60
	s_cselect_b32 s34, s54, s59
	s_add_u32 s56, s26, s56
	s_addc_u32 s59, s27, 0
	s_add_u32 s56, s56, 0x100
	s_addc_u32 s59, s59, 0
	s_and_b64 s[30:31], s[30:31], exec
	s_cselect_b32 s31, s17, s59
	s_cselect_b32 s30, s55, s56
	s_add_u32 s56, s57, 0x10080
	s_addc_u32 s57, s58, 0
	s_add_i32 m0, s25, 0xc000
	ds_read_b128 v[178:181], v145
	ds_read_b128 v[182:185], v145 offset:1024
	ds_read_b128 v[186:189], v145 offset:2048
	ds_read_b128 v[190:193], v145 offset:3072
	ds_read_b128 v[194:197], v145 offset:4096
	ds_read_b128 v[198:201], v145 offset:5120
	ds_read_b128 v[206:209], v145 offset:6144
	ds_read_b128 v[210:213], v145 offset:7168
	global_load_lds_dwordx4 v134, s[56:57]
	s_add_i32 m0, s25, 0xe000
	s_nop 0
	global_load_lds_dwordx4 v130, s[56:57]
	s_waitcnt vmcnt(8)
	s_waitcnt lgkmcnt(0)
	s_barrier
	s_setprio 1
	s_waitcnt lgkmcnt(0)
	v_mfma_f32_16x16x32_bf16 v[124:127], v[146:149], v[178:181], v[124:127]
	v_mfma_f32_16x16x32_bf16 v[120:123], v[154:157], v[178:181], v[120:123]
	v_mfma_f32_16x16x32_bf16 v[116:119], v[146:149], v[186:189], v[116:119]
	v_mfma_f32_16x16x32_bf16 v[112:115], v[154:157], v[186:189], v[112:115]
	v_mfma_f32_16x16x32_bf16 v[108:111], v[146:149], v[194:197], v[108:111]
	v_mfma_f32_16x16x32_bf16 v[104:107], v[154:157], v[194:197], v[104:107]
	v_mfma_f32_16x16x32_bf16 v[100:103], v[146:149], v[206:209], v[100:103]
	v_mfma_f32_16x16x32_bf16 v[96:99], v[154:157], v[206:209], v[96:99]
	v_mfma_f32_16x16x32_bf16 v[124:127], v[150:153], v[182:185], v[124:127]
	v_mfma_f32_16x16x32_bf16 v[120:123], v[158:161], v[182:185], v[120:123]
	v_mfma_f32_16x16x32_bf16 v[116:119], v[150:153], v[190:193], v[116:119]
	v_mfma_f32_16x16x32_bf16 v[112:115], v[158:161], v[190:193], v[112:115]
	v_mfma_f32_16x16x32_bf16 v[108:111], v[150:153], v[198:201], v[108:111]
	v_mfma_f32_16x16x32_bf16 v[104:107], v[158:161], v[198:201], v[104:107]
	v_mfma_f32_16x16x32_bf16 v[100:103], v[150:153], v[210:213], v[100:103]
	v_mfma_f32_16x16x32_bf16 v[96:99], v[158:161], v[210:213], v[96:99]
	s_setprio 0
	s_setprio 1
	v_mfma_f32_16x16x32_bf16 v[76:79], v[162:165], v[178:181], v[76:79]
	v_mfma_f32_16x16x32_bf16 v[68:71], v[170:173], v[178:181], v[68:71]
	v_mfma_f32_16x16x32_bf16 v[60:63], v[162:165], v[186:189], v[60:63]
	v_mfma_f32_16x16x32_bf16 v[52:55], v[170:173], v[186:189], v[52:55]
	v_mfma_f32_16x16x32_bf16 v[44:47], v[162:165], v[194:197], v[44:47]
	v_mfma_f32_16x16x32_bf16 v[40:43], v[170:173], v[194:197], v[40:43]
	v_mfma_f32_16x16x32_bf16 v[36:39], v[162:165], v[206:209], v[36:39]
	v_mfma_f32_16x16x32_bf16 v[32:35], v[170:173], v[206:209], v[32:35]
	v_mfma_f32_16x16x32_bf16 v[76:79], v[166:169], v[182:185], v[76:79]
	v_mfma_f32_16x16x32_bf16 v[68:71], v[174:177], v[182:185], v[68:71]
	v_mfma_f32_16x16x32_bf16 v[60:63], v[166:169], v[190:193], v[60:63]
	v_mfma_f32_16x16x32_bf16 v[52:55], v[174:177], v[190:193], v[52:55]
	v_mfma_f32_16x16x32_bf16 v[44:47], v[166:169], v[198:201], v[44:47]
	v_mfma_f32_16x16x32_bf16 v[40:43], v[174:177], v[198:201], v[40:43]
	v_mfma_f32_16x16x32_bf16 v[36:39], v[166:169], v[210:213], v[36:39]
	v_mfma_f32_16x16x32_bf16 v[32:35], v[174:177], v[210:213], v[32:35]
	s_setprio 0
	s_barrier
	s_add_i32 s56, s50, s93
	s_mov_b32 m0, s56
	ds_read_b128 v[178:181], v145 offset:16384
	ds_read_b128 v[182:185], v145 offset:17408
	ds_read_b128 v[186:189], v145 offset:18432
	ds_read_b128 v[190:193], v145 offset:19456
	ds_read_b128 v[194:197], v145 offset:20480
	ds_read_b128 v[198:201], v145 offset:21504
	ds_read_b128 v[206:209], v145 offset:22528
	ds_read_b128 v[210:213], v145 offset:23552
	global_load_lds_dwordx4 v132, s[30:31]
	s_add_i32 m0, s56, 0x2000
	s_add_u32 s56, s30, 0x10000
	v_lshl_add_u64 v[214:215], s[30:31], 0, v[128:129]
	s_addc_u32 s57, s31, 0
	s_add_i32 s58, s51, s93
	global_load_lds_dwordx4 v128, s[30:31]
	s_mov_b32 m0, s58
	v_lshl_add_u64 v[218:219], s[34:35], 0, v[130:131]
	global_load_lds_dwordx4 v132, s[56:57]
	s_add_i32 m0, s58, 0x2000
	s_nop 0
	global_load_lds_dwordx4 v128, s[56:57]
	v_lshl_add_u64 v[216:217], s[34:35], 0, v[134:135]
	s_mov_b32 m0, s25
	s_nop 0
	global_load_lds_dwordx4 v134, s[34:35]
	s_mov_b32 m0, s44
	s_nop 0
	global_load_lds_dwordx4 v130, s[34:35]
	s_waitcnt vmcnt(8)
	s_waitcnt lgkmcnt(0)
	s_barrier
	s_setprio 1
	s_waitcnt lgkmcnt(0)
	v_mfma_f32_16x16x32_bf16 v[92:95], v[146:149], v[178:181], v[92:95]
	v_mfma_f32_16x16x32_bf16 v[88:91], v[154:157], v[178:181], v[88:91]
	v_mfma_f32_16x16x32_bf16 v[84:87], v[146:149], v[186:189], v[84:87]
	v_mfma_f32_16x16x32_bf16 v[80:83], v[154:157], v[186:189], v[80:83]
	v_mfma_f32_16x16x32_bf16 v[72:75], v[146:149], v[194:197], v[72:75]
	v_mfma_f32_16x16x32_bf16 v[64:67], v[154:157], v[194:197], v[64:67]
	v_mfma_f32_16x16x32_bf16 v[56:59], v[146:149], v[206:209], v[56:59]
	v_mfma_f32_16x16x32_bf16 v[48:51], v[154:157], v[206:209], v[48:51]
	v_mfma_f32_16x16x32_bf16 v[92:95], v[150:153], v[182:185], v[92:95]
	v_mfma_f32_16x16x32_bf16 v[88:91], v[158:161], v[182:185], v[88:91]
	v_mfma_f32_16x16x32_bf16 v[84:87], v[150:153], v[190:193], v[84:87]
	v_mfma_f32_16x16x32_bf16 v[80:83], v[158:161], v[190:193], v[80:83]
	v_mfma_f32_16x16x32_bf16 v[72:75], v[150:153], v[198:201], v[72:75]
	v_mfma_f32_16x16x32_bf16 v[64:67], v[158:161], v[198:201], v[64:67]
	v_mfma_f32_16x16x32_bf16 v[56:59], v[150:153], v[210:213], v[56:59]
	v_mfma_f32_16x16x32_bf16 v[48:51], v[158:161], v[210:213], v[48:51]
	s_setprio 0
	s_setprio 1
	v_mfma_f32_16x16x32_bf16 v[28:31], v[162:165], v[178:181], v[28:31]
	v_mfma_f32_16x16x32_bf16 v[24:27], v[170:173], v[178:181], v[24:27]
	v_mfma_f32_16x16x32_bf16 v[20:23], v[162:165], v[186:189], v[20:23]
	v_mfma_f32_16x16x32_bf16 v[16:19], v[170:173], v[186:189], v[16:19]
	v_mfma_f32_16x16x32_bf16 v[12:15], v[162:165], v[194:197], v[12:15]
	v_mfma_f32_16x16x32_bf16 v[8:11], v[170:173], v[194:197], v[8:11]
	v_mfma_f32_16x16x32_bf16 v[4:7], v[162:165], v[206:209], v[4:7]
	v_mfma_f32_16x16x32_bf16 v[0:3], v[170:173], v[206:209], v[0:3]
	v_mfma_f32_16x16x32_bf16 v[28:31], v[166:169], v[182:185], v[28:31]
	v_mfma_f32_16x16x32_bf16 v[24:27], v[174:177], v[182:185], v[24:27]
	v_mfma_f32_16x16x32_bf16 v[20:23], v[166:169], v[190:193], v[20:23]
	v_mfma_f32_16x16x32_bf16 v[16:19], v[174:177], v[190:193], v[16:19]
	v_mfma_f32_16x16x32_bf16 v[12:15], v[166:169], v[198:201], v[12:15]
	v_mfma_f32_16x16x32_bf16 v[8:11], v[174:177], v[198:201], v[8:11]
	v_mfma_f32_16x16x32_bf16 v[4:7], v[166:169], v[210:213], v[4:7]
	v_mfma_f32_16x16x32_bf16 v[0:3], v[174:177], v[210:213], v[0:3]
	s_setprio 0
	s_barrier
	s_add_i32 s56, 0, 0x18000
	s_add_i32 s57, 0, 0x1c000
	v_add_u32_e32 v158, s56, v141
	v_add_u32_e32 v174, s57, v141
	ds_read_b128 v[146:149], v158
	ds_read_b128 v[150:153], v158 offset:1024
	ds_read_b128 v[154:157], v158 offset:2048
	ds_read_b128 v[158:161], v158 offset:3072
	ds_read_b128 v[162:165], v174
	ds_read_b128 v[166:169], v174 offset:1024
	ds_read_b128 v[170:173], v174 offset:2048
	ds_read_b128 v[174:177], v174 offset:3072
	s_add_u32 s34, s34, 0x10000
	s_addc_u32 s35, s35, 0
	s_mov_b32 m0, s45
	ds_read_b128 v[178:181], v145 offset:32768
	ds_read_b128 v[182:185], v145 offset:33792
	ds_read_b128 v[186:189], v145 offset:34816
	ds_read_b128 v[190:193], v145 offset:35840
	ds_read_b128 v[194:197], v145 offset:36864
	ds_read_b128 v[198:201], v145 offset:37888
	ds_read_b128 v[206:209], v145 offset:38912
	ds_read_b128 v[210:213], v145 offset:39936
	global_load_lds_dwordx4 v134, s[34:35]
	s_mov_b32 m0, s46
	s_nop 0
	global_load_lds_dwordx4 v130, s[34:35]
	s_waitcnt vmcnt(8)
	s_waitcnt lgkmcnt(0)
	s_barrier
	s_setprio 1
	s_waitcnt lgkmcnt(0)
	v_mfma_f32_16x16x32_bf16 v[124:127], v[146:149], v[178:181], v[124:127]
	v_mfma_f32_16x16x32_bf16 v[120:123], v[154:157], v[178:181], v[120:123]
	v_mfma_f32_16x16x32_bf16 v[116:119], v[146:149], v[186:189], v[116:119]
	v_mfma_f32_16x16x32_bf16 v[112:115], v[154:157], v[186:189], v[112:115]
	v_mfma_f32_16x16x32_bf16 v[108:111], v[146:149], v[194:197], v[108:111]
	v_mfma_f32_16x16x32_bf16 v[104:107], v[154:157], v[194:197], v[104:107]
	v_mfma_f32_16x16x32_bf16 v[100:103], v[146:149], v[206:209], v[100:103]
	v_mfma_f32_16x16x32_bf16 v[96:99], v[154:157], v[206:209], v[96:99]
	v_mfma_f32_16x16x32_bf16 v[124:127], v[150:153], v[182:185], v[124:127]
	v_mfma_f32_16x16x32_bf16 v[120:123], v[158:161], v[182:185], v[120:123]
	v_mfma_f32_16x16x32_bf16 v[116:119], v[150:153], v[190:193], v[116:119]
	v_mfma_f32_16x16x32_bf16 v[112:115], v[158:161], v[190:193], v[112:115]
	v_mfma_f32_16x16x32_bf16 v[108:111], v[150:153], v[198:201], v[108:111]
	v_mfma_f32_16x16x32_bf16 v[104:107], v[158:161], v[198:201], v[104:107]
	v_mfma_f32_16x16x32_bf16 v[100:103], v[150:153], v[210:213], v[100:103]
	v_mfma_f32_16x16x32_bf16 v[96:99], v[158:161], v[210:213], v[96:99]
	s_setprio 0
	s_setprio 1
	v_mfma_f32_16x16x32_bf16 v[76:79], v[162:165], v[178:181], v[76:79]
	v_mfma_f32_16x16x32_bf16 v[68:71], v[170:173], v[178:181], v[68:71]
	v_mfma_f32_16x16x32_bf16 v[60:63], v[162:165], v[186:189], v[60:63]
	v_mfma_f32_16x16x32_bf16 v[52:55], v[170:173], v[186:189], v[52:55]
	v_mfma_f32_16x16x32_bf16 v[44:47], v[162:165], v[194:197], v[44:47]
	v_mfma_f32_16x16x32_bf16 v[40:43], v[170:173], v[194:197], v[40:43]
	v_mfma_f32_16x16x32_bf16 v[36:39], v[162:165], v[206:209], v[36:39]
	v_mfma_f32_16x16x32_bf16 v[32:35], v[170:173], v[206:209], v[32:35]
	v_mfma_f32_16x16x32_bf16 v[76:79], v[166:169], v[182:185], v[76:79]
	v_mfma_f32_16x16x32_bf16 v[68:71], v[174:177], v[182:185], v[68:71]
	v_mfma_f32_16x16x32_bf16 v[60:63], v[166:169], v[190:193], v[60:63]
	v_mfma_f32_16x16x32_bf16 v[52:55], v[174:177], v[190:193], v[52:55]
	v_mfma_f32_16x16x32_bf16 v[44:47], v[166:169], v[198:201], v[44:47]
	v_mfma_f32_16x16x32_bf16 v[40:43], v[174:177], v[198:201], v[40:43]
	v_mfma_f32_16x16x32_bf16 v[36:39], v[166:169], v[210:213], v[36:39]
	v_mfma_f32_16x16x32_bf16 v[32:35], v[174:177], v[210:213], v[32:35]
	s_setprio 0
	s_barrier
	s_add_i32 s34, s56, s93
	s_add_i32 m0, s34, 0xffffff80
	ds_read_b128 v[178:181], v145 offset:49152
	ds_read_b128 v[182:185], v145 offset:50176
	ds_read_b128 v[186:189], v145 offset:51200
	ds_read_b128 v[190:193], v145 offset:52224
	ds_read_b128 v[194:197], v145 offset:53248
	ds_read_b128 v[198:201], v145 offset:54272
	ds_read_b128 v[206:209], v145 offset:55296
	ds_read_b128 v[210:213], v145 offset:56320
	global_load_lds_dwordx4 v132, s[30:31] offset:128
	s_add_i32 m0, s34, 0x2000
	s_add_u32 s30, s30, 0x10080
	v_lshl_add_u64 v[202:203], v[214:215], 0, s[10:11]
	s_addc_u32 s31, s31, 0
	s_add_i32 s34, s57, s93
	global_load_lds_dwordx4 v[202:203], off
	s_mov_b32 m0, s34
	s_nop 0
	global_load_lds_dwordx4 v132, s[30:31]
	s_add_i32 m0, s34, 0x2000
	s_nop 0
	global_load_lds_dwordx4 v128, s[30:31]
	v_lshl_add_u64 v[202:203], v[216:217], 0, s[10:11]
	s_mov_b32 m0, s48
	s_nop 0
	global_load_lds_dwordx4 v[202:203], off
	v_lshl_add_u64 v[202:203], v[218:219], 0, s[10:11]
	s_mov_b32 m0, s49
	s_nop 0
	global_load_lds_dwordx4 v[202:203], off
	s_waitcnt vmcnt(8)
	s_waitcnt lgkmcnt(0)
	s_barrier
	s_setprio 1
	s_waitcnt lgkmcnt(0)
	v_mfma_f32_16x16x32_bf16 v[92:95], v[146:149], v[178:181], v[92:95]
	v_mfma_f32_16x16x32_bf16 v[88:91], v[154:157], v[178:181], v[88:91]
	v_mfma_f32_16x16x32_bf16 v[84:87], v[146:149], v[186:189], v[84:87]
	v_mfma_f32_16x16x32_bf16 v[80:83], v[154:157], v[186:189], v[80:83]
	v_mfma_f32_16x16x32_bf16 v[72:75], v[146:149], v[194:197], v[72:75]
	v_mfma_f32_16x16x32_bf16 v[64:67], v[154:157], v[194:197], v[64:67]
	v_mfma_f32_16x16x32_bf16 v[56:59], v[146:149], v[206:209], v[56:59]
	v_mfma_f32_16x16x32_bf16 v[48:51], v[154:157], v[206:209], v[48:51]
	v_mfma_f32_16x16x32_bf16 v[92:95], v[150:153], v[182:185], v[92:95]
	v_mfma_f32_16x16x32_bf16 v[88:91], v[158:161], v[182:185], v[88:91]
	v_mfma_f32_16x16x32_bf16 v[84:87], v[150:153], v[190:193], v[84:87]
	v_mfma_f32_16x16x32_bf16 v[80:83], v[158:161], v[190:193], v[80:83]
	v_mfma_f32_16x16x32_bf16 v[72:75], v[150:153], v[198:201], v[72:75]
	v_mfma_f32_16x16x32_bf16 v[64:67], v[158:161], v[198:201], v[64:67]
	v_mfma_f32_16x16x32_bf16 v[56:59], v[150:153], v[210:213], v[56:59]
	v_mfma_f32_16x16x32_bf16 v[48:51], v[158:161], v[210:213], v[48:51]
	s_setprio 0
	s_setprio 1
	v_mfma_f32_16x16x32_bf16 v[28:31], v[162:165], v[178:181], v[28:31]
	v_mfma_f32_16x16x32_bf16 v[24:27], v[170:173], v[178:181], v[24:27]
	v_mfma_f32_16x16x32_bf16 v[20:23], v[162:165], v[186:189], v[20:23]
	v_mfma_f32_16x16x32_bf16 v[16:19], v[170:173], v[186:189], v[16:19]
	v_mfma_f32_16x16x32_bf16 v[12:15], v[162:165], v[194:197], v[12:15]
	v_mfma_f32_16x16x32_bf16 v[8:11], v[170:173], v[194:197], v[8:11]
	v_mfma_f32_16x16x32_bf16 v[4:7], v[162:165], v[206:209], v[4:7]
	v_mfma_f32_16x16x32_bf16 v[0:3], v[170:173], v[206:209], v[0:3]
	v_mfma_f32_16x16x32_bf16 v[28:31], v[166:169], v[182:185], v[28:31]
	v_mfma_f32_16x16x32_bf16 v[24:27], v[174:177], v[182:185], v[24:27]
	v_mfma_f32_16x16x32_bf16 v[20:23], v[166:169], v[190:193], v[20:23]
	v_mfma_f32_16x16x32_bf16 v[16:19], v[174:177], v[190:193], v[16:19]
	v_mfma_f32_16x16x32_bf16 v[12:15], v[166:169], v[198:201], v[12:15]
	v_mfma_f32_16x16x32_bf16 v[8:11], v[174:177], v[198:201], v[8:11]
	v_mfma_f32_16x16x32_bf16 v[4:7], v[166:169], v[210:213], v[4:7]
	v_mfma_f32_16x16x32_bf16 v[0:3], v[174:177], v[210:213], v[0:3]
	s_setprio 0
	s_barrier
	s_movk_i32 s56, 0x100
	s_and_b64 vcc, exec, s[0:1]
	s_mov_b64 s[30:31], -1
	s_mov_b64 s[0:1], 0
	s_cbranch_vccnz .LBB0_971
	s_andn2_b64 vcc, exec, s[94:95]
	s_cbranch_vccnz .LBB0_974
	s_barrier
